# up epilogue: tiles outside the context group zero their edge registers once and skip the per-block LDS edge reads and selects
# speedup vs baseline: 1.0015x; 1.0015x over previous
.LUPE_noex:
	s_cbranch_vccnz .LUPE_er0
	v_mov_b32_e32 v172, 0
	v_mov_b32_e32 v173, 0
	v_mov_b32_e32 v174, 0
	v_mov_b32_e32 v175, 0
	v_mov_b32_e32 v176, 0
	v_mov_b32_e32 v177, 0
	v_mov_b32_e32 v178, 0
	v_mov_b32_e32 v179, 0
	v_mov_b32_e32 v180, 0
	v_mov_b32_e32 v181, 0
	v_mov_b32_e32 v182, 0
	v_mov_b32_e32 v183, 0
	v_mov_b32_e32 v184, 0
	v_mov_b32_e32 v185, 0
	v_mov_b32_e32 v186, 0
	v_mov_b32_e32 v187, 0
	s_branch .LUPE_er0x

.LUPE_er0x:
	s_waitcnt vmcnt(0) lgkmcnt(0)
	s_cbranch_vccz .LUPE_nsel1
	v_cndmask_b32_e64 v172, 0, v172, s[52:53]
	v_cndmask_b32_e64 v173, 0, v173, s[52:53]
	v_cndmask_b32_e64 v174, 0, v174, s[52:53]
	v_cndmask_b32_e64 v175, 0, v175, s[52:53]
	v_cndmask_b32_e64 v176, 0, v176, s[52:53]
	v_cndmask_b32_e64 v177, 0, v177, s[52:53]
	v_cndmask_b32_e64 v178, 0, v178, s[52:53]
	v_cndmask_b32_e64 v179, 0, v179, s[52:53]
.LUPE_nsel1:
	v_pk_fma_f32 v[228:229], v[136:137], v[116:117], v[140:141]
	v_pk_fma_f32 v[230:231], v[138:139], v[118:119], v[142:143]
	v_pk_fma_f32 v[232:233], v[152:153], v[112:113], v[156:157]
	v_pk_fma_f32 v[234:235], v[154:155], v[114:115], v[158:159]
	v_pk_fma_f32 v[228:229], v[132:133], v[124:125], v[228:229]
	v_pk_fma_f32 v[230:231], v[134:135], v[126:127], v[230:231]
	v_pk_fma_f32 v[232:233], v[148:149], v[120:121], v[232:233]
	v_pk_fma_f32 v[234:235], v[150:151], v[122:123], v[234:235]
	v_mov_b32_dpp v172, v100 row_shr:1 row_mask:0xf bank_mask:0xf
	v_mov_b32_dpp v173, v101 row_shr:1 row_mask:0xf bank_mask:0xf
	v_mov_b32_dpp v174, v102 row_shr:1 row_mask:0xf bank_mask:0xf
	v_mov_b32_dpp v175, v103 row_shr:1 row_mask:0xf bank_mask:0xf
	v_mov_b32_dpp v176, v96 row_shr:1 row_mask:0xf bank_mask:0xf
	v_mov_b32_dpp v177, v97 row_shr:1 row_mask:0xf bank_mask:0xf
	v_mov_b32_dpp v178, v98 row_shr:1 row_mask:0xf bank_mask:0xf
	v_mov_b32_dpp v179, v99 row_shr:1 row_mask:0xf bank_mask:0xf
	v_pk_fma_f32 v[228:229], v[128:129], v[172:173], v[228:229]
	v_pk_fma_f32 v[230:231], v[130:131], v[174:175], v[230:231]
	v_pk_fma_f32 v[232:233], v[144:145], v[176:177], v[232:233]
	v_pk_fma_f32 v[234:235], v[146:147], v[178:179], v[234:235]
	v_pk_mul_f32 v[216:217], v[228:229], v[220:221]
	v_pk_mul_f32 v[218:219], v[230:231], v[220:221]
	v_exp_f32_e32 v216, v216
	v_exp_f32_e32 v217, v217
	v_exp_f32_e32 v218, v218
	v_exp_f32_e32 v219, v219
	v_pk_add_f32 v[216:217], v[216:217], v[222:223]
	v_pk_add_f32 v[218:219], v[218:219], v[222:223]
	v_rcp_f32_e32 v216, v216
	v_rcp_f32_e32 v217, v217
	v_rcp_f32_e32 v218, v218
	v_rcp_f32_e32 v219, v219
	v_pk_mul_f32 v[228:229], v[228:229], v[216:217]
	v_pk_mul_f32 v[230:231], v[230:231], v[218:219]
	v_pk_mul_f32 v[228:229], v[232:233], v[228:229]
	v_pk_mul_f32 v[230:231], v[234:235], v[230:231]
	s_mov_b64 s[8:9], s[90:91]
	v_cvt_pk_bf16_f32 v224, v228, v229
	v_cvt_pk_bf16_f32 v225, v230, v231
	global_store_dwordx2 v237, v[224:225], s[8:9]
	s_cbranch_vccz .LUPE_er1
	ds_read_b128 v[172:175], v226 offset:512
	ds_read_b128 v[176:179], v226 offset:640
.LUPE_er1:
	v_pk_fma_f32 v[228:229], v[136:137], v[108:109], v[140:141]
	v_pk_fma_f32 v[230:231], v[138:139], v[110:111], v[142:143]
	v_pk_fma_f32 v[232:233], v[152:153], v[104:105], v[156:157]
	v_pk_fma_f32 v[234:235], v[154:155], v[106:107], v[158:159]
	v_pk_fma_f32 v[228:229], v[132:133], v[116:117], v[228:229]
	v_pk_fma_f32 v[230:231], v[134:135], v[118:119], v[230:231]
	v_pk_fma_f32 v[232:233], v[148:149], v[112:113], v[232:233]
	v_pk_fma_f32 v[234:235], v[150:151], v[114:115], v[234:235]
	v_pk_fma_f32 v[228:229], v[128:129], v[124:125], v[228:229]
	v_pk_fma_f32 v[230:231], v[130:131], v[126:127], v[230:231]
	v_pk_fma_f32 v[232:233], v[144:145], v[120:121], v[232:233]
	v_pk_fma_f32 v[234:235], v[146:147], v[122:123], v[234:235]
	v_pk_mul_f32 v[216:217], v[228:229], v[220:221]
	v_pk_mul_f32 v[218:219], v[230:231], v[220:221]
	v_exp_f32_e32 v216, v216
	v_exp_f32_e32 v217, v217
	v_exp_f32_e32 v218, v218
	v_exp_f32_e32 v219, v219
	v_pk_add_f32 v[216:217], v[216:217], v[222:223]
	v_pk_add_f32 v[218:219], v[218:219], v[222:223]
	v_rcp_f32_e32 v216, v216
	v_rcp_f32_e32 v217, v217
	v_rcp_f32_e32 v218, v218
	v_rcp_f32_e32 v219, v219
	v_pk_mul_f32 v[228:229], v[228:229], v[216:217]
	v_pk_mul_f32 v[230:231], v[230:231], v[218:219]
	v_pk_mul_f32 v[228:229], v[232:233], v[228:229]
	v_pk_mul_f32 v[230:231], v[234:235], v[230:231]
	s_add_u32 s8, s90, 0x1600
	s_addc_u32 s9, s91, 0
	v_cvt_pk_bf16_f32 v224, v228, v229
	v_cvt_pk_bf16_f32 v225, v230, v231
	global_store_dwordx2 v237, v[224:225], s[8:9]
	v_pk_fma_f32 v[228:229], v[136:137], v[100:101], v[140:141]
	v_pk_fma_f32 v[230:231], v[138:139], v[102:103], v[142:143]
	v_pk_fma_f32 v[232:233], v[152:153], v[96:97], v[156:157]
	v_pk_fma_f32 v[234:235], v[154:155], v[98:99], v[158:159]
	v_pk_fma_f32 v[228:229], v[132:133], v[108:109], v[228:229]
	v_pk_fma_f32 v[230:231], v[134:135], v[110:111], v[230:231]
	v_pk_fma_f32 v[232:233], v[148:149], v[104:105], v[232:233]
	v_pk_fma_f32 v[234:235], v[150:151], v[106:107], v[234:235]
	v_pk_fma_f32 v[228:229], v[128:129], v[116:117], v[228:229]
	v_pk_fma_f32 v[230:231], v[130:131], v[118:119], v[230:231]
	v_pk_fma_f32 v[232:233], v[144:145], v[112:113], v[232:233]
	v_pk_fma_f32 v[234:235], v[146:147], v[114:115], v[234:235]
	v_pk_mul_f32 v[216:217], v[228:229], v[220:221]
	v_pk_mul_f32 v[218:219], v[230:231], v[220:221]
	v_exp_f32_e32 v216, v216
	v_exp_f32_e32 v217, v217
	v_exp_f32_e32 v218, v218
	v_exp_f32_e32 v219, v219
	v_pk_add_f32 v[216:217], v[216:217], v[222:223]
	v_pk_add_f32 v[218:219], v[218:219], v[222:223]
	v_rcp_f32_e32 v216, v216
	v_rcp_f32_e32 v217, v217
	v_rcp_f32_e32 v218, v218
	v_rcp_f32_e32 v219, v219
	v_pk_mul_f32 v[228:229], v[228:229], v[216:217]
	v_pk_mul_f32 v[230:231], v[230:231], v[218:219]
	v_pk_mul_f32 v[228:229], v[232:233], v[228:229]
	v_pk_mul_f32 v[230:231], v[234:235], v[230:231]
	s_add_u32 s8, s90, 0x2c00
	s_addc_u32 s9, s91, 0
	v_cvt_pk_bf16_f32 v224, v228, v229
	v_cvt_pk_bf16_f32 v225, v230, v231
	global_store_dwordx2 v237, v[224:225], s[8:9]
	v_mov_b32_dpp v180, v124 row_shl:1 row_mask:0xf bank_mask:0xf
	v_mov_b32_dpp v181, v125 row_shl:1 row_mask:0xf bank_mask:0xf
	v_mov_b32_dpp v182, v126 row_shl:1 row_mask:0xf bank_mask:0xf
	v_mov_b32_dpp v183, v127 row_shl:1 row_mask:0xf bank_mask:0xf
	v_mov_b32_dpp v184, v120 row_shl:1 row_mask:0xf bank_mask:0xf
	v_mov_b32_dpp v185, v121 row_shl:1 row_mask:0xf bank_mask:0xf
	v_mov_b32_dpp v186, v122 row_shl:1 row_mask:0xf bank_mask:0xf
	v_mov_b32_dpp v187, v123 row_shl:1 row_mask:0xf bank_mask:0xf
	v_pk_fma_f32 v[228:229], v[136:137], v[180:181], v[140:141]
	v_pk_fma_f32 v[230:231], v[138:139], v[182:183], v[142:143]
	v_pk_fma_f32 v[232:233], v[152:153], v[184:185], v[156:157]
	v_pk_fma_f32 v[234:235], v[154:155], v[186:187], v[158:159]
	s_cbranch_vccz .LUPE_er2
	ds_read_b128 v[180:183], v226 offset:768
	ds_read_b128 v[184:187], v226 offset:896
.LUPE_er2:
	v_pk_fma_f32 v[228:229], v[132:133], v[100:101], v[228:229]
	v_pk_fma_f32 v[230:231], v[134:135], v[102:103], v[230:231]
	v_pk_fma_f32 v[232:233], v[148:149], v[96:97], v[232:233]
	v_pk_fma_f32 v[234:235], v[150:151], v[98:99], v[234:235]
	v_pk_fma_f32 v[228:229], v[128:129], v[108:109], v[228:229]
	v_pk_fma_f32 v[230:231], v[130:131], v[110:111], v[230:231]
	v_pk_fma_f32 v[232:233], v[144:145], v[104:105], v[232:233]
	v_pk_fma_f32 v[234:235], v[146:147], v[106:107], v[234:235]
	v_pk_mul_f32 v[216:217], v[228:229], v[220:221]
	v_pk_mul_f32 v[218:219], v[230:231], v[220:221]
	v_exp_f32_e32 v216, v216
	v_exp_f32_e32 v217, v217
	v_exp_f32_e32 v218, v218
	v_exp_f32_e32 v219, v219
	v_pk_add_f32 v[216:217], v[216:217], v[222:223]
	v_pk_add_f32 v[218:219], v[218:219], v[222:223]
	v_rcp_f32_e32 v216, v216
	v_rcp_f32_e32 v217, v217
	v_rcp_f32_e32 v218, v218
	v_rcp_f32_e32 v219, v219
	v_pk_mul_f32 v[228:229], v[228:229], v[216:217]
	v_pk_mul_f32 v[230:231], v[230:231], v[218:219]
	v_pk_mul_f32 v[228:229], v[232:233], v[228:229]
	v_pk_mul_f32 v[230:231], v[234:235], v[230:231]
	s_add_u32 s8, s90, 0x4200
	s_addc_u32 s9, s91, 0
	v_cvt_pk_bf16_f32 v224, v228, v229
	v_cvt_pk_bf16_f32 v225, v230, v231
	global_store_dwordx2 v237, v[224:225], s[8:9]
	global_load_dwordx4 v[96:99], v227, s[76:77] offset:16
	global_load_dwordx4 v[112:115], v236, s[76:77] offset:16
	global_load_dwordx4 v[100:103], v227, s[80:81] offset:16
	global_load_dwordx4 v[116:119], v236, s[80:81] offset:16
	global_load_dwordx4 v[104:107], v227, s[86:87] offset:16
	global_load_dwordx4 v[120:123], v236, s[86:87] offset:16
	global_load_dwordx4 v[108:111], v227, s[4:5] offset:16
	global_load_dwordx4 v[124:127], v236, s[4:5] offset:16
	s_waitcnt lgkmcnt(0)
	s_cbranch_vccz .LUPE_nsel2
	v_cndmask_b32_e64 v180, 0, v180, s[68:69]
	v_cndmask_b32_e64 v181, 0, v181, s[68:69]
	v_cndmask_b32_e64 v182, 0, v182, s[68:69]
	v_cndmask_b32_e64 v183, 0, v183, s[68:69]
	v_cndmask_b32_e64 v184, 0, v184, s[68:69]
	v_cndmask_b32_e64 v185, 0, v185, s[68:69]
	v_cndmask_b32_e64 v186, 0, v186, s[68:69]
	v_cndmask_b32_e64 v187, 0, v187, s[68:69]
.LUPE_nsel2:
	v_pk_fma_f32 v[228:229], v[136:137], v[84:85], v[140:141]
	v_pk_fma_f32 v[230:231], v[138:139], v[86:87], v[142:143]
	v_pk_fma_f32 v[232:233], v[152:153], v[80:81], v[156:157]
	v_pk_fma_f32 v[234:235], v[154:155], v[82:83], v[158:159]
	v_pk_fma_f32 v[228:229], v[132:133], v[92:93], v[228:229]
	v_pk_fma_f32 v[230:231], v[134:135], v[94:95], v[230:231]
	v_pk_fma_f32 v[232:233], v[148:149], v[88:89], v[232:233]
	v_pk_fma_f32 v[234:235], v[150:151], v[90:91], v[234:235]
	v_mov_b32_dpp v172, v72 row_shr:1 row_mask:0xf bank_mask:0xf
	v_mov_b32_dpp v173, v73 row_shr:1 row_mask:0xf bank_mask:0xf
	v_mov_b32_dpp v174, v74 row_shr:1 row_mask:0xf bank_mask:0xf
	v_mov_b32_dpp v175, v75 row_shr:1 row_mask:0xf bank_mask:0xf
	v_mov_b32_dpp v176, v64 row_shr:1 row_mask:0xf bank_mask:0xf
	v_mov_b32_dpp v177, v65 row_shr:1 row_mask:0xf bank_mask:0xf
	v_mov_b32_dpp v178, v66 row_shr:1 row_mask:0xf bank_mask:0xf
	v_mov_b32_dpp v179, v67 row_shr:1 row_mask:0xf bank_mask:0xf
	v_pk_fma_f32 v[228:229], v[128:129], v[172:173], v[228:229]
	v_pk_fma_f32 v[230:231], v[130:131], v[174:175], v[230:231]
	v_pk_fma_f32 v[232:233], v[144:145], v[176:177], v[232:233]
	v_pk_fma_f32 v[234:235], v[146:147], v[178:179], v[234:235]
	v_pk_mul_f32 v[216:217], v[228:229], v[220:221]
	v_pk_mul_f32 v[218:219], v[230:231], v[220:221]
	v_exp_f32_e32 v216, v216
	v_exp_f32_e32 v217, v217
	v_exp_f32_e32 v218, v218
	v_exp_f32_e32 v219, v219
	v_pk_add_f32 v[216:217], v[216:217], v[222:223]
	v_pk_add_f32 v[218:219], v[218:219], v[222:223]
	v_rcp_f32_e32 v216, v216
	v_rcp_f32_e32 v217, v217
	v_rcp_f32_e32 v218, v218
	v_rcp_f32_e32 v219, v219
	v_pk_mul_f32 v[228:229], v[228:229], v[216:217]
	v_pk_mul_f32 v[230:231], v[230:231], v[218:219]
	v_pk_mul_f32 v[228:229], v[232:233], v[228:229]
	v_pk_mul_f32 v[230:231], v[234:235], v[230:231]
	s_add_u32 s8, s90, 0xb0000
	s_addc_u32 s9, s91, 0
	v_cvt_pk_bf16_f32 v224, v228, v229
	v_cvt_pk_bf16_f32 v225, v230, v231
	global_store_dwordx2 v237, v[224:225], s[8:9]
	s_cbranch_vccz .LUPE_er3
	ds_read_b128 v[172:175], v226 offset:64
	ds_read_b128 v[176:179], v226 offset:192
.LUPE_er3:
	v_pk_fma_f32 v[228:229], v[136:137], v[76:77], v[140:141]
	v_pk_fma_f32 v[230:231], v[138:139], v[78:79], v[142:143]
	v_pk_fma_f32 v[232:233], v[152:153], v[68:69], v[156:157]
	v_pk_fma_f32 v[234:235], v[154:155], v[70:71], v[158:159]
	v_pk_fma_f32 v[228:229], v[132:133], v[84:85], v[228:229]
	v_pk_fma_f32 v[230:231], v[134:135], v[86:87], v[230:231]
	v_pk_fma_f32 v[232:233], v[148:149], v[80:81], v[232:233]
	v_pk_fma_f32 v[234:235], v[150:151], v[82:83], v[234:235]
	v_pk_fma_f32 v[228:229], v[128:129], v[92:93], v[228:229]
	v_pk_fma_f32 v[230:231], v[130:131], v[94:95], v[230:231]
	v_pk_fma_f32 v[232:233], v[144:145], v[88:89], v[232:233]
	v_pk_fma_f32 v[234:235], v[146:147], v[90:91], v[234:235]
	v_pk_mul_f32 v[216:217], v[228:229], v[220:221]
	v_pk_mul_f32 v[218:219], v[230:231], v[220:221]
	v_exp_f32_e32 v216, v216
	v_exp_f32_e32 v217, v217
	v_exp_f32_e32 v218, v218
	v_exp_f32_e32 v219, v219
	v_pk_add_f32 v[216:217], v[216:217], v[222:223]
	v_pk_add_f32 v[218:219], v[218:219], v[222:223]
	v_rcp_f32_e32 v216, v216
	v_rcp_f32_e32 v217, v217
	v_rcp_f32_e32 v218, v218
	v_rcp_f32_e32 v219, v219
	v_pk_mul_f32 v[228:229], v[228:229], v[216:217]
	v_pk_mul_f32 v[230:231], v[230:231], v[218:219]
	v_pk_mul_f32 v[228:229], v[232:233], v[228:229]
	v_pk_mul_f32 v[230:231], v[234:235], v[230:231]
	s_add_u32 s8, s90, 0xb1600
	s_addc_u32 s9, s91, 0
	v_cvt_pk_bf16_f32 v224, v228, v229
	v_cvt_pk_bf16_f32 v225, v230, v231
	global_store_dwordx2 v237, v[224:225], s[8:9]
	v_pk_fma_f32 v[228:229], v[136:137], v[72:73], v[140:141]
	v_pk_fma_f32 v[230:231], v[138:139], v[74:75], v[142:143]
	v_pk_fma_f32 v[232:233], v[152:153], v[64:65], v[156:157]
	v_pk_fma_f32 v[234:235], v[154:155], v[66:67], v[158:159]
	v_pk_fma_f32 v[228:229], v[132:133], v[76:77], v[228:229]
	v_pk_fma_f32 v[230:231], v[134:135], v[78:79], v[230:231]
	v_pk_fma_f32 v[232:233], v[148:149], v[68:69], v[232:233]
	v_pk_fma_f32 v[234:235], v[150:151], v[70:71], v[234:235]
	v_pk_fma_f32 v[228:229], v[128:129], v[84:85], v[228:229]
	v_pk_fma_f32 v[230:231], v[130:131], v[86:87], v[230:231]
	v_pk_fma_f32 v[232:233], v[144:145], v[80:81], v[232:233]
	v_pk_fma_f32 v[234:235], v[146:147], v[82:83], v[234:235]
	v_pk_mul_f32 v[216:217], v[228:229], v[220:221]
	v_pk_mul_f32 v[218:219], v[230:231], v[220:221]
	v_exp_f32_e32 v216, v216
	v_exp_f32_e32 v217, v217
	v_exp_f32_e32 v218, v218
	v_exp_f32_e32 v219, v219
	v_pk_add_f32 v[216:217], v[216:217], v[222:223]
	v_pk_add_f32 v[218:219], v[218:219], v[222:223]
	v_rcp_f32_e32 v216, v216
	v_rcp_f32_e32 v217, v217
	v_rcp_f32_e32 v218, v218
	v_rcp_f32_e32 v219, v219
	v_pk_mul_f32 v[228:229], v[228:229], v[216:217]
	v_pk_mul_f32 v[230:231], v[230:231], v[218:219]
	v_pk_mul_f32 v[228:229], v[232:233], v[228:229]
	v_pk_mul_f32 v[230:231], v[234:235], v[230:231]
	s_add_u32 s8, s90, 0xb2c00
	s_addc_u32 s9, s91, 0
	v_cvt_pk_bf16_f32 v224, v228, v229
	v_cvt_pk_bf16_f32 v225, v230, v231
	global_store_dwordx2 v237, v[224:225], s[8:9]
	v_mov_b32_dpp v180, v92 row_shl:1 row_mask:0xf bank_mask:0xf
	v_mov_b32_dpp v181, v93 row_shl:1 row_mask:0xf bank_mask:0xf
	v_mov_b32_dpp v182, v94 row_shl:1 row_mask:0xf bank_mask:0xf
	v_mov_b32_dpp v183, v95 row_shl:1 row_mask:0xf bank_mask:0xf
	v_mov_b32_dpp v184, v88 row_shl:1 row_mask:0xf bank_mask:0xf
	v_mov_b32_dpp v185, v89 row_shl:1 row_mask:0xf bank_mask:0xf
	v_mov_b32_dpp v186, v90 row_shl:1 row_mask:0xf bank_mask:0xf
	v_mov_b32_dpp v187, v91 row_shl:1 row_mask:0xf bank_mask:0xf
	v_pk_fma_f32 v[228:229], v[136:137], v[180:181], v[140:141]
	v_pk_fma_f32 v[230:231], v[138:139], v[182:183], v[142:143]
	v_pk_fma_f32 v[232:233], v[152:153], v[184:185], v[156:157]
	v_pk_fma_f32 v[234:235], v[154:155], v[186:187], v[158:159]
	s_cbranch_vccz .LUPE_er4
	ds_read_b128 v[180:183], v226 offset:320
	ds_read_b128 v[184:187], v226 offset:448
.LUPE_er4:
	v_pk_fma_f32 v[228:229], v[132:133], v[72:73], v[228:229]
	v_pk_fma_f32 v[230:231], v[134:135], v[74:75], v[230:231]
	v_pk_fma_f32 v[232:233], v[148:149], v[64:65], v[232:233]
	v_pk_fma_f32 v[234:235], v[150:151], v[66:67], v[234:235]
	v_pk_fma_f32 v[228:229], v[128:129], v[76:77], v[228:229]
	v_pk_fma_f32 v[230:231], v[130:131], v[78:79], v[230:231]
	v_pk_fma_f32 v[232:233], v[144:145], v[68:69], v[232:233]
	v_pk_fma_f32 v[234:235], v[146:147], v[70:71], v[234:235]
	v_pk_mul_f32 v[216:217], v[228:229], v[220:221]
	v_pk_mul_f32 v[218:219], v[230:231], v[220:221]
	v_exp_f32_e32 v216, v216
	v_exp_f32_e32 v217, v217
	v_exp_f32_e32 v218, v218
	v_exp_f32_e32 v219, v219
	v_pk_add_f32 v[216:217], v[216:217], v[222:223]
	v_pk_add_f32 v[218:219], v[218:219], v[222:223]
	v_rcp_f32_e32 v216, v216
	v_rcp_f32_e32 v217, v217
	v_rcp_f32_e32 v218, v218
	v_rcp_f32_e32 v219, v219
	v_pk_mul_f32 v[228:229], v[228:229], v[216:217]
	v_pk_mul_f32 v[230:231], v[230:231], v[218:219]
	v_pk_mul_f32 v[228:229], v[232:233], v[228:229]
	v_pk_mul_f32 v[230:231], v[234:235], v[230:231]
	s_add_u32 s8, s90, 0xb4200
	s_addc_u32 s9, s91, 0
	v_cvt_pk_bf16_f32 v224, v228, v229
	v_cvt_pk_bf16_f32 v225, v230, v231
	global_store_dwordx2 v237, v[224:225], s[8:9]
	s_waitcnt vmcnt(4) lgkmcnt(0)
	s_cbranch_vccz .LUPE_nsel3
	v_cndmask_b32_e64 v172, 0, v172, s[52:53]
	v_cndmask_b32_e64 v173, 0, v173, s[52:53]
	v_cndmask_b32_e64 v174, 0, v174, s[52:53]
	v_cndmask_b32_e64 v175, 0, v175, s[52:53]
	v_cndmask_b32_e64 v176, 0, v176, s[52:53]
	v_cndmask_b32_e64 v177, 0, v177, s[52:53]
	v_cndmask_b32_e64 v178, 0, v178, s[52:53]
	v_cndmask_b32_e64 v179, 0, v179, s[52:53]
.LUPE_nsel3:
	v_pk_fma_f32 v[228:229], v[104:105], v[52:53], v[108:109]
	v_pk_fma_f32 v[230:231], v[106:107], v[54:55], v[110:111]
	v_pk_fma_f32 v[232:233], v[120:121], v[48:49], v[124:125]
	v_pk_fma_f32 v[234:235], v[122:123], v[50:51], v[126:127]
	v_pk_fma_f32 v[228:229], v[100:101], v[60:61], v[228:229]
	v_pk_fma_f32 v[230:231], v[102:103], v[62:63], v[230:231]
	v_pk_fma_f32 v[232:233], v[116:117], v[56:57], v[232:233]
	v_pk_fma_f32 v[234:235], v[118:119], v[58:59], v[234:235]
	v_mov_b32_dpp v172, v36 row_shr:1 row_mask:0xf bank_mask:0xf
	v_mov_b32_dpp v173, v37 row_shr:1 row_mask:0xf bank_mask:0xf
	v_mov_b32_dpp v174, v38 row_shr:1 row_mask:0xf bank_mask:0xf
	v_mov_b32_dpp v175, v39 row_shr:1 row_mask:0xf bank_mask:0xf
	v_mov_b32_dpp v176, v32 row_shr:1 row_mask:0xf bank_mask:0xf
	v_mov_b32_dpp v177, v33 row_shr:1 row_mask:0xf bank_mask:0xf
	v_mov_b32_dpp v178, v34 row_shr:1 row_mask:0xf bank_mask:0xf
	v_mov_b32_dpp v179, v35 row_shr:1 row_mask:0xf bank_mask:0xf
	v_pk_fma_f32 v[228:229], v[96:97], v[172:173], v[228:229]
	v_pk_fma_f32 v[230:231], v[98:99], v[174:175], v[230:231]
	v_pk_fma_f32 v[232:233], v[112:113], v[176:177], v[232:233]
	v_pk_fma_f32 v[234:235], v[114:115], v[178:179], v[234:235]
	v_pk_mul_f32 v[216:217], v[228:229], v[220:221]
	v_pk_mul_f32 v[218:219], v[230:231], v[220:221]
	v_exp_f32_e32 v216, v216
	v_exp_f32_e32 v217, v217
	v_exp_f32_e32 v218, v218
	v_exp_f32_e32 v219, v219
	v_pk_add_f32 v[216:217], v[216:217], v[222:223]
	v_pk_add_f32 v[218:219], v[218:219], v[222:223]
	v_rcp_f32_e32 v216, v216
	v_rcp_f32_e32 v217, v217
	v_rcp_f32_e32 v218, v218
	v_rcp_f32_e32 v219, v219
	v_pk_mul_f32 v[228:229], v[228:229], v[216:217]
	v_pk_mul_f32 v[230:231], v[230:231], v[218:219]
	v_pk_mul_f32 v[228:229], v[232:233], v[228:229]
	v_pk_mul_f32 v[230:231], v[234:235], v[230:231]
	s_mov_b64 s[8:9], s[90:91]
	v_cvt_pk_bf16_f32 v224, v228, v229
	v_cvt_pk_bf16_f32 v225, v230, v231
	global_store_dwordx2 v237, v[224:225], s[8:9] offset:8
	s_cbranch_vccz .LUPE_er5
	ds_read_b128 v[172:175], v226 offset:576
	ds_read_b128 v[176:179], v226 offset:704
.LUPE_er5:
	v_pk_fma_f32 v[228:229], v[104:105], v[44:45], v[108:109]
	v_pk_fma_f32 v[230:231], v[106:107], v[46:47], v[110:111]
	v_pk_fma_f32 v[232:233], v[120:121], v[40:41], v[124:125]
	v_pk_fma_f32 v[234:235], v[122:123], v[42:43], v[126:127]
	v_pk_fma_f32 v[228:229], v[100:101], v[52:53], v[228:229]
	v_pk_fma_f32 v[230:231], v[102:103], v[54:55], v[230:231]
	v_pk_fma_f32 v[232:233], v[116:117], v[48:49], v[232:233]
	v_pk_fma_f32 v[234:235], v[118:119], v[50:51], v[234:235]
	v_pk_fma_f32 v[228:229], v[96:97], v[60:61], v[228:229]
	v_pk_fma_f32 v[230:231], v[98:99], v[62:63], v[230:231]
	v_pk_fma_f32 v[232:233], v[112:113], v[56:57], v[232:233]
	v_pk_fma_f32 v[234:235], v[114:115], v[58:59], v[234:235]
	v_pk_mul_f32 v[216:217], v[228:229], v[220:221]
	v_pk_mul_f32 v[218:219], v[230:231], v[220:221]
	v_exp_f32_e32 v216, v216
	v_exp_f32_e32 v217, v217
	v_exp_f32_e32 v218, v218
	v_exp_f32_e32 v219, v219
	v_pk_add_f32 v[216:217], v[216:217], v[222:223]
	v_pk_add_f32 v[218:219], v[218:219], v[222:223]
	v_rcp_f32_e32 v216, v216
	v_rcp_f32_e32 v217, v217
	v_rcp_f32_e32 v218, v218
	v_rcp_f32_e32 v219, v219
	v_pk_mul_f32 v[228:229], v[228:229], v[216:217]
	v_pk_mul_f32 v[230:231], v[230:231], v[218:219]
	v_pk_mul_f32 v[228:229], v[232:233], v[228:229]
	v_pk_mul_f32 v[230:231], v[234:235], v[230:231]
	s_add_u32 s8, s90, 0x1600
	s_addc_u32 s9, s91, 0
	v_cvt_pk_bf16_f32 v224, v228, v229
	v_cvt_pk_bf16_f32 v225, v230, v231
	global_store_dwordx2 v237, v[224:225], s[8:9] offset:8
	v_pk_fma_f32 v[228:229], v[104:105], v[36:37], v[108:109]
	v_pk_fma_f32 v[230:231], v[106:107], v[38:39], v[110:111]
	v_pk_fma_f32 v[232:233], v[120:121], v[32:33], v[124:125]
	v_pk_fma_f32 v[234:235], v[122:123], v[34:35], v[126:127]
	v_pk_fma_f32 v[228:229], v[100:101], v[44:45], v[228:229]
	v_pk_fma_f32 v[230:231], v[102:103], v[46:47], v[230:231]
	v_pk_fma_f32 v[232:233], v[116:117], v[40:41], v[232:233]
	v_pk_fma_f32 v[234:235], v[118:119], v[42:43], v[234:235]
	v_pk_fma_f32 v[228:229], v[96:97], v[52:53], v[228:229]
	v_pk_fma_f32 v[230:231], v[98:99], v[54:55], v[230:231]
	v_pk_fma_f32 v[232:233], v[112:113], v[48:49], v[232:233]
	v_pk_fma_f32 v[234:235], v[114:115], v[50:51], v[234:235]
	v_pk_mul_f32 v[216:217], v[228:229], v[220:221]
	v_pk_mul_f32 v[218:219], v[230:231], v[220:221]
	v_exp_f32_e32 v216, v216
	v_exp_f32_e32 v217, v217
	v_exp_f32_e32 v218, v218
	v_exp_f32_e32 v219, v219
	v_pk_add_f32 v[216:217], v[216:217], v[222:223]
	v_pk_add_f32 v[218:219], v[218:219], v[222:223]
	v_rcp_f32_e32 v216, v216
	v_rcp_f32_e32 v217, v217
	v_rcp_f32_e32 v218, v218
	v_rcp_f32_e32 v219, v219
	v_pk_mul_f32 v[228:229], v[228:229], v[216:217]
	v_pk_mul_f32 v[230:231], v[230:231], v[218:219]
	v_pk_mul_f32 v[228:229], v[232:233], v[228:229]
	v_pk_mul_f32 v[230:231], v[234:235], v[230:231]
	s_add_u32 s8, s90, 0x2c00
	s_addc_u32 s9, s91, 0
	v_cvt_pk_bf16_f32 v224, v228, v229
	v_cvt_pk_bf16_f32 v225, v230, v231
	global_store_dwordx2 v237, v[224:225], s[8:9] offset:8
	v_mov_b32_dpp v180, v60 row_shl:1 row_mask:0xf bank_mask:0xf
	v_mov_b32_dpp v181, v61 row_shl:1 row_mask:0xf bank_mask:0xf
	v_mov_b32_dpp v182, v62 row_shl:1 row_mask:0xf bank_mask:0xf
	v_mov_b32_dpp v183, v63 row_shl:1 row_mask:0xf bank_mask:0xf
	v_mov_b32_dpp v184, v56 row_shl:1 row_mask:0xf bank_mask:0xf
	v_mov_b32_dpp v185, v57 row_shl:1 row_mask:0xf bank_mask:0xf
	v_mov_b32_dpp v186, v58 row_shl:1 row_mask:0xf bank_mask:0xf
	v_mov_b32_dpp v187, v59 row_shl:1 row_mask:0xf bank_mask:0xf
	v_pk_fma_f32 v[228:229], v[104:105], v[180:181], v[108:109]
	v_pk_fma_f32 v[230:231], v[106:107], v[182:183], v[110:111]
	v_pk_fma_f32 v[232:233], v[120:121], v[184:185], v[124:125]
	v_pk_fma_f32 v[234:235], v[122:123], v[186:187], v[126:127]
	s_cbranch_vccz .LUPE_er6
	ds_read_b128 v[180:183], v226 offset:832
	ds_read_b128 v[184:187], v226 offset:960
.LUPE_er6:
	v_pk_fma_f32 v[228:229], v[100:101], v[36:37], v[228:229]
	v_pk_fma_f32 v[230:231], v[102:103], v[38:39], v[230:231]
	v_pk_fma_f32 v[232:233], v[116:117], v[32:33], v[232:233]
	v_pk_fma_f32 v[234:235], v[118:119], v[34:35], v[234:235]
	v_pk_fma_f32 v[228:229], v[96:97], v[44:45], v[228:229]
	v_pk_fma_f32 v[230:231], v[98:99], v[46:47], v[230:231]
	v_pk_fma_f32 v[232:233], v[112:113], v[40:41], v[232:233]
	v_pk_fma_f32 v[234:235], v[114:115], v[42:43], v[234:235]
	v_pk_mul_f32 v[216:217], v[228:229], v[220:221]
	v_pk_mul_f32 v[218:219], v[230:231], v[220:221]
	v_exp_f32_e32 v216, v216
	v_exp_f32_e32 v217, v217
	v_exp_f32_e32 v218, v218
	v_exp_f32_e32 v219, v219
	v_pk_add_f32 v[216:217], v[216:217], v[222:223]
	v_pk_add_f32 v[218:219], v[218:219], v[222:223]
	v_rcp_f32_e32 v216, v216
	v_rcp_f32_e32 v217, v217
	v_rcp_f32_e32 v218, v218
	v_rcp_f32_e32 v219, v219
	v_pk_mul_f32 v[228:229], v[228:229], v[216:217]
	v_pk_mul_f32 v[230:231], v[230:231], v[218:219]
	v_pk_mul_f32 v[228:229], v[232:233], v[228:229]
	v_pk_mul_f32 v[230:231], v[234:235], v[230:231]
	s_add_u32 s8, s90, 0x4200
	s_addc_u32 s9, s91, 0
	v_cvt_pk_bf16_f32 v224, v228, v229
	v_cvt_pk_bf16_f32 v225, v230, v231
	global_store_dwordx2 v237, v[224:225], s[8:9] offset:8
	s_waitcnt lgkmcnt(0)
	s_cbranch_vccz .LUPE_nsel4
	v_cndmask_b32_e64 v180, 0, v180, s[68:69]
	v_cndmask_b32_e64 v181, 0, v181, s[68:69]
	v_cndmask_b32_e64 v182, 0, v182, s[68:69]
	v_cndmask_b32_e64 v183, 0, v183, s[68:69]
	v_cndmask_b32_e64 v184, 0, v184, s[68:69]
	v_cndmask_b32_e64 v185, 0, v185, s[68:69]
	v_cndmask_b32_e64 v186, 0, v186, s[68:69]
	v_cndmask_b32_e64 v187, 0, v187, s[68:69]
.LUPE_nsel4:
	v_pk_fma_f32 v[228:229], v[104:105], v[20:21], v[108:109]
	v_pk_fma_f32 v[230:231], v[106:107], v[22:23], v[110:111]
	v_pk_fma_f32 v[232:233], v[120:121], v[16:17], v[124:125]
	v_pk_fma_f32 v[234:235], v[122:123], v[18:19], v[126:127]
	v_pk_fma_f32 v[228:229], v[100:101], v[28:29], v[228:229]
	v_pk_fma_f32 v[230:231], v[102:103], v[30:31], v[230:231]
	v_pk_fma_f32 v[232:233], v[116:117], v[24:25], v[232:233]
	v_pk_fma_f32 v[234:235], v[118:119], v[26:27], v[234:235]
	v_mov_b32_dpp v172, v4 row_shr:1 row_mask:0xf bank_mask:0xf
	v_mov_b32_dpp v173, v5 row_shr:1 row_mask:0xf bank_mask:0xf
	v_mov_b32_dpp v174, v6 row_shr:1 row_mask:0xf bank_mask:0xf
	v_mov_b32_dpp v175, v7 row_shr:1 row_mask:0xf bank_mask:0xf
	v_mov_b32_dpp v176, v0 row_shr:1 row_mask:0xf bank_mask:0xf
	v_mov_b32_dpp v177, v1 row_shr:1 row_mask:0xf bank_mask:0xf
	v_mov_b32_dpp v178, v2 row_shr:1 row_mask:0xf bank_mask:0xf
	v_mov_b32_dpp v179, v3 row_shr:1 row_mask:0xf bank_mask:0xf
	v_pk_fma_f32 v[228:229], v[96:97], v[172:173], v[228:229]
	v_pk_fma_f32 v[230:231], v[98:99], v[174:175], v[230:231]
	v_pk_fma_f32 v[232:233], v[112:113], v[176:177], v[232:233]
	v_pk_fma_f32 v[234:235], v[114:115], v[178:179], v[234:235]
	v_pk_mul_f32 v[216:217], v[228:229], v[220:221]
	v_pk_mul_f32 v[218:219], v[230:231], v[220:221]
	v_exp_f32_e32 v216, v216
	v_exp_f32_e32 v217, v217
	v_exp_f32_e32 v218, v218
	v_exp_f32_e32 v219, v219
	v_pk_add_f32 v[216:217], v[216:217], v[222:223]
	v_pk_add_f32 v[218:219], v[218:219], v[222:223]
	v_rcp_f32_e32 v216, v216
	v_rcp_f32_e32 v217, v217
	v_rcp_f32_e32 v218, v218
	v_rcp_f32_e32 v219, v219
	v_pk_mul_f32 v[228:229], v[228:229], v[216:217]
	v_pk_mul_f32 v[230:231], v[230:231], v[218:219]
	v_pk_mul_f32 v[228:229], v[232:233], v[228:229]
	v_pk_mul_f32 v[230:231], v[234:235], v[230:231]
	s_add_u32 s8, s90, 0xb0000
	s_addc_u32 s9, s91, 0
	v_cvt_pk_bf16_f32 v224, v228, v229
	v_cvt_pk_bf16_f32 v225, v230, v231
	global_store_dwordx2 v237, v[224:225], s[8:9] offset:8
	v_pk_fma_f32 v[228:229], v[104:105], v[12:13], v[108:109]
	v_pk_fma_f32 v[230:231], v[106:107], v[14:15], v[110:111]
	v_pk_fma_f32 v[232:233], v[120:121], v[8:9], v[124:125]
	v_pk_fma_f32 v[234:235], v[122:123], v[10:11], v[126:127]
	v_pk_fma_f32 v[228:229], v[100:101], v[20:21], v[228:229]
	v_pk_fma_f32 v[230:231], v[102:103], v[22:23], v[230:231]
	v_pk_fma_f32 v[232:233], v[116:117], v[16:17], v[232:233]
	v_pk_fma_f32 v[234:235], v[118:119], v[18:19], v[234:235]
	v_pk_fma_f32 v[228:229], v[96:97], v[28:29], v[228:229]
	v_pk_fma_f32 v[230:231], v[98:99], v[30:31], v[230:231]
	v_pk_fma_f32 v[232:233], v[112:113], v[24:25], v[232:233]
	v_pk_fma_f32 v[234:235], v[114:115], v[26:27], v[234:235]
	v_pk_mul_f32 v[216:217], v[228:229], v[220:221]
	v_pk_mul_f32 v[218:219], v[230:231], v[220:221]
	v_exp_f32_e32 v216, v216
	v_exp_f32_e32 v217, v217
	v_exp_f32_e32 v218, v218
	v_exp_f32_e32 v219, v219
	v_pk_add_f32 v[216:217], v[216:217], v[222:223]
	v_pk_add_f32 v[218:219], v[218:219], v[222:223]
	v_rcp_f32_e32 v216, v216
	v_rcp_f32_e32 v217, v217
	v_rcp_f32_e32 v218, v218
	v_rcp_f32_e32 v219, v219
	v_pk_mul_f32 v[228:229], v[228:229], v[216:217]
	v_pk_mul_f32 v[230:231], v[230:231], v[218:219]
	v_pk_mul_f32 v[228:229], v[232:233], v[228:229]
	v_pk_mul_f32 v[230:231], v[234:235], v[230:231]
	s_add_u32 s8, s90, 0xb1600
	s_addc_u32 s9, s91, 0
	v_cvt_pk_bf16_f32 v224, v228, v229
	v_cvt_pk_bf16_f32 v225, v230, v231
	global_store_dwordx2 v237, v[224:225], s[8:9] offset:8
	v_pk_fma_f32 v[228:229], v[104:105], v[4:5], v[108:109]
	v_pk_fma_f32 v[230:231], v[106:107], v[6:7], v[110:111]
	v_pk_fma_f32 v[232:233], v[120:121], v[0:1], v[124:125]
	v_pk_fma_f32 v[234:235], v[122:123], v[2:3], v[126:127]
	v_pk_fma_f32 v[228:229], v[100:101], v[12:13], v[228:229]
	v_pk_fma_f32 v[230:231], v[102:103], v[14:15], v[230:231]
	v_pk_fma_f32 v[232:233], v[116:117], v[8:9], v[232:233]
	v_pk_fma_f32 v[234:235], v[118:119], v[10:11], v[234:235]
	v_pk_fma_f32 v[228:229], v[96:97], v[20:21], v[228:229]
	v_pk_fma_f32 v[230:231], v[98:99], v[22:23], v[230:231]
	v_pk_fma_f32 v[232:233], v[112:113], v[16:17], v[232:233]
	v_pk_fma_f32 v[234:235], v[114:115], v[18:19], v[234:235]
	v_pk_mul_f32 v[216:217], v[228:229], v[220:221]
	v_pk_mul_f32 v[218:219], v[230:231], v[220:221]
	v_exp_f32_e32 v216, v216
	v_exp_f32_e32 v217, v217
	v_exp_f32_e32 v218, v218
	v_exp_f32_e32 v219, v219
	v_pk_add_f32 v[216:217], v[216:217], v[222:223]
	v_pk_add_f32 v[218:219], v[218:219], v[222:223]
	v_rcp_f32_e32 v216, v216
	v_rcp_f32_e32 v217, v217
	v_rcp_f32_e32 v218, v218
	v_rcp_f32_e32 v219, v219
	v_pk_mul_f32 v[228:229], v[228:229], v[216:217]
	v_pk_mul_f32 v[230:231], v[230:231], v[218:219]
	v_pk_mul_f32 v[228:229], v[232:233], v[228:229]
	v_pk_mul_f32 v[230:231], v[234:235], v[230:231]
	s_add_u32 s8, s90, 0xb2c00
	s_addc_u32 s9, s91, 0
	v_cvt_pk_bf16_f32 v224, v228, v229
	v_cvt_pk_bf16_f32 v225, v230, v231
	global_store_dwordx2 v237, v[224:225], s[8:9] offset:8
	v_mov_b32_dpp v180, v28 row_shl:1 row_mask:0xf bank_mask:0xf
	v_mov_b32_dpp v181, v29 row_shl:1 row_mask:0xf bank_mask:0xf
	v_mov_b32_dpp v182, v30 row_shl:1 row_mask:0xf bank_mask:0xf
	v_mov_b32_dpp v183, v31 row_shl:1 row_mask:0xf bank_mask:0xf
	v_mov_b32_dpp v184, v24 row_shl:1 row_mask:0xf bank_mask:0xf
	v_mov_b32_dpp v185, v25 row_shl:1 row_mask:0xf bank_mask:0xf
	v_mov_b32_dpp v186, v26 row_shl:1 row_mask:0xf bank_mask:0xf
	v_mov_b32_dpp v187, v27 row_shl:1 row_mask:0xf bank_mask:0xf
	v_pk_fma_f32 v[228:229], v[104:105], v[180:181], v[108:109]
	v_pk_fma_f32 v[230:231], v[106:107], v[182:183], v[110:111]
	v_pk_fma_f32 v[232:233], v[120:121], v[184:185], v[124:125]
	v_pk_fma_f32 v[234:235], v[122:123], v[186:187], v[126:127]
	v_pk_fma_f32 v[228:229], v[100:101], v[4:5], v[228:229]
	v_pk_fma_f32 v[230:231], v[102:103], v[6:7], v[230:231]
	v_pk_fma_f32 v[232:233], v[116:117], v[0:1], v[232:233]
	v_pk_fma_f32 v[234:235], v[118:119], v[2:3], v[234:235]
	v_pk_fma_f32 v[228:229], v[96:97], v[12:13], v[228:229]
	v_pk_fma_f32 v[230:231], v[98:99], v[14:15], v[230:231]
	v_pk_fma_f32 v[232:233], v[112:113], v[8:9], v[232:233]
	v_pk_fma_f32 v[234:235], v[114:115], v[10:11], v[234:235]
	v_pk_mul_f32 v[216:217], v[228:229], v[220:221]
	v_pk_mul_f32 v[218:219], v[230:231], v[220:221]
	v_exp_f32_e32 v216, v216
	v_exp_f32_e32 v217, v217
	v_exp_f32_e32 v218, v218
	v_exp_f32_e32 v219, v219
	v_pk_add_f32 v[216:217], v[216:217], v[222:223]
	v_pk_add_f32 v[218:219], v[218:219], v[222:223]
	v_rcp_f32_e32 v216, v216
	v_rcp_f32_e32 v217, v217
	v_rcp_f32_e32 v218, v218
	v_rcp_f32_e32 v219, v219
	v_pk_mul_f32 v[228:229], v[228:229], v[216:217]
	v_pk_mul_f32 v[230:231], v[230:231], v[218:219]
	v_pk_mul_f32 v[228:229], v[232:233], v[228:229]
	v_pk_mul_f32 v[230:231], v[234:235], v[230:231]
	s_add_u32 s8, s90, 0xb4200
	s_addc_u32 s9, s91, 0
	v_cvt_pk_bf16_f32 v224, v228, v229
	v_cvt_pk_bf16_f32 v225, v230, v231
	global_store_dwordx2 v237, v[224:225], s[8:9] offset:8
	s_andn2_b64 vcc, exec, s[82:83]
	s_mov_b64 s[4:5], -1
	s_cbranch_vccnz .LBB0_43
	s_andn2_b64 vcc, exec, s[88:89]
	s_cbranch_vccnz .LBB0_42
	s_barrier
	s_branch .LBB0_42
